# FFN up-projection units: dedicated swiglu epilogue with one per-lane store offset plus scalar base steps and batched exp/rcp groups (same arithmetic and layout as before)
# speedup vs baseline: 1.0008x; 1.0008x over previous
; __device__ __forceinline__ unsigned cvtpk(float lo, float hi) { f32x2 v = {lo, hi}; bf16x2_t b = __builtin_convertvector(v, bf16x2_t); return __builtin_bit_cast(unsigned, b); }
; __device__ __forceinline__ float sigmoidf_(float x) { return fast_rcp(1.f + __expf(-x)); }
;     __device__ __forceinline__ void operator()(const f32x4 (&acc)[2][2][4][2], const Unit& u, int wr, int wc, int fr, int fq) const {
;     ...
;         if (mode == 2) {
;             const int par = fq & 1;
; #pragma unroll
;             for (int ai = 0; ai < 2; ++ai)
; #pragma unroll
;                 for (int bj = 0; bj < 2; ++bj) { const int acol = ((u.pn * BM + bj * HALF + wc * 32) >> 1) + 4 * (fq - par);
; #pragma unroll
;                     for (int mp = 0; mp < 4; mp += 2) {
;                         u32x2 wk[2];
; #pragma unroll
;                         for (int q = 0; q < 2; ++q) { const f32x4 v0 = acc[ai][bj][mp + q][0], v1 = acc[ai][bj][mp + q][1]; float r[4];
; #pragma unroll
;                             for (int e = 0; e < 4; ++e) r[e] = v0[e] * sigmoidf_(v0[e]) * v1[e];
;                             wk[q].x = cvtpk(r[0], r[1]); wk[q].y = cvtpk(r[2], r[3]); }
;                         const auto sx = __builtin_amdgcn_permlane16_swap(wk[0].x, wk[1].x, false, false);
;                         const auto sy = __builtin_amdgcn_permlane16_swap(wk[0].y, wk[1].y, false, false);
;                         u32x4 w; w.x = sx[0]; w.y = sy[0]; w.z = sx[1]; w.w = sy[1];
;                         const size_t row = (size_t)(u.pm * BM + rl0 + ai * HALF + (mp + par) * 16);
;                         *(u32x4*)(O + row * ldc + acol) = w; } }
.Lepi2:
	s_lshl_b32 s74, s0, 1
	v_bfe_u32 v229, v150, 3, 1
	v_lshl_add_u32 v228, v229, 4, v184
	v_mul_lo_u32 v228, v228, s74
	v_add_u32_e32 v228, v228, v150
	v_lshlrev_b32_e32 v229, 3, v229
	v_sub_u32_e32 v228, v228, v229
	s_lshl_b32 s75, s68, 8
	s_mul_hi_u32 s77, s75, s74
	s_mul_i32 s76, s75, s74
	s_add_u32 s78, s24, s76
	s_addc_u32 s79, s25, s77
	s_lshl_b32 s75, s69, 8
	s_add_u32 s78, s78, s75
	s_addc_u32 s79, s79, 0
	s_lshl_b32 s81, s74, 5
	s_lshl_b32 s80, s74, 7
	s_mov_b32 s90, s78
	s_mov_b32 s91, s79
	v_mul_f32_e32 v136, 0xbfb8aa3b, v132
	v_mul_f32_e32 v137, 0xbfb8aa3b, v133
	v_mul_f32_e32 v138, 0xbfb8aa3b, v134
	v_mul_f32_e32 v139, 0xbfb8aa3b, v135
	v_mul_f32_e32 v140, 0xbfb8aa3b, v124
	v_mul_f32_e32 v141, 0xbfb8aa3b, v125
	v_mul_f32_e32 v142, 0xbfb8aa3b, v126
	v_mul_f32_e32 v143, 0xbfb8aa3b, v127
	v_exp_f32_e32 v136, v136
	v_exp_f32_e32 v137, v137
	v_exp_f32_e32 v138, v138
	v_exp_f32_e32 v139, v139
	v_exp_f32_e32 v140, v140
	v_exp_f32_e32 v141, v141
	v_exp_f32_e32 v142, v142
	v_exp_f32_e32 v143, v143
	v_add_f32_e32 v136, 1.0, v136
	v_add_f32_e32 v137, 1.0, v137
	v_add_f32_e32 v138, 1.0, v138
	v_add_f32_e32 v139, 1.0, v139
	v_add_f32_e32 v140, 1.0, v140
	v_add_f32_e32 v141, 1.0, v141
	v_add_f32_e32 v142, 1.0, v142
	v_add_f32_e32 v143, 1.0, v143
	v_rcp_f32_e32 v136, v136
	v_rcp_f32_e32 v137, v137
	v_rcp_f32_e32 v138, v138
	v_rcp_f32_e32 v139, v139
	v_rcp_f32_e32 v140, v140
	v_rcp_f32_e32 v141, v141
	v_rcp_f32_e32 v142, v142
	v_rcp_f32_e32 v143, v143
	v_mul_f32_e32 v136, v132, v136
	v_mul_f32_e32 v137, v133, v137
	v_mul_f32_e32 v138, v134, v138
	v_mul_f32_e32 v139, v135, v139
	v_mul_f32_e32 v140, v124, v140
	v_mul_f32_e32 v141, v125, v141
	v_mul_f32_e32 v142, v126, v142
	v_mul_f32_e32 v143, v127, v143
	v_mul_f32_e32 v136, v128, v136
	v_mul_f32_e32 v137, v129, v137
	v_mul_f32_e32 v138, v130, v138
	v_mul_f32_e32 v139, v131, v139
	v_mul_f32_e32 v140, v120, v140
	v_mul_f32_e32 v141, v121, v141
	v_mul_f32_e32 v142, v122, v142
	v_mul_f32_e32 v143, v123, v143
	v_cvt_pk_bf16_f32 v246, v136, v137
	v_cvt_pk_bf16_f32 v247, v138, v139
	v_cvt_pk_bf16_f32 v248, v140, v141
	v_cvt_pk_bf16_f32 v249, v142, v143
	s_nop 1
	v_permlane16_swap_b32_e32 v246, v248
	v_permlane16_swap_b32_e32 v247, v249
	s_nop 1
	global_store_dwordx4 v228, v[246:249], s[90:91]
	v_mul_f32_e32 v136, 0xbfb8aa3b, v100
	v_mul_f32_e32 v137, 0xbfb8aa3b, v101
	v_mul_f32_e32 v138, 0xbfb8aa3b, v102
	v_mul_f32_e32 v139, 0xbfb8aa3b, v103
	v_mul_f32_e32 v140, 0xbfb8aa3b, v92
	v_mul_f32_e32 v141, 0xbfb8aa3b, v93
	v_mul_f32_e32 v142, 0xbfb8aa3b, v94
	v_mul_f32_e32 v143, 0xbfb8aa3b, v95
	v_exp_f32_e32 v136, v136
	v_exp_f32_e32 v137, v137
	v_exp_f32_e32 v138, v138
	v_exp_f32_e32 v139, v139
	v_exp_f32_e32 v140, v140
	v_exp_f32_e32 v141, v141
	v_exp_f32_e32 v142, v142
	v_exp_f32_e32 v143, v143
	v_add_f32_e32 v136, 1.0, v136
	v_add_f32_e32 v137, 1.0, v137
	v_add_f32_e32 v138, 1.0, v138
	v_add_f32_e32 v139, 1.0, v139
	v_add_f32_e32 v140, 1.0, v140
	v_add_f32_e32 v141, 1.0, v141
	v_add_f32_e32 v142, 1.0, v142
	v_add_f32_e32 v143, 1.0, v143
	v_rcp_f32_e32 v136, v136
	v_rcp_f32_e32 v137, v137
	v_rcp_f32_e32 v138, v138
	v_rcp_f32_e32 v139, v139
	v_rcp_f32_e32 v140, v140
	v_rcp_f32_e32 v141, v141
	v_rcp_f32_e32 v142, v142
	v_rcp_f32_e32 v143, v143
	v_mul_f32_e32 v136, v100, v136
	v_mul_f32_e32 v137, v101, v137
	v_mul_f32_e32 v138, v102, v138
	v_mul_f32_e32 v139, v103, v139
	v_mul_f32_e32 v140, v92, v140
	v_mul_f32_e32 v141, v93, v141
	v_mul_f32_e32 v142, v94, v142
	v_mul_f32_e32 v143, v95, v143
	v_mul_f32_e32 v136, v96, v136
	v_mul_f32_e32 v137, v97, v137
	v_mul_f32_e32 v138, v98, v138
	v_mul_f32_e32 v139, v99, v139
	v_mul_f32_e32 v140, v88, v140
	v_mul_f32_e32 v141, v89, v141
	v_mul_f32_e32 v142, v90, v142
	v_mul_f32_e32 v143, v91, v143
	v_cvt_pk_bf16_f32 v210, v136, v137
	v_cvt_pk_bf16_f32 v211, v138, v139
	v_cvt_pk_bf16_f32 v212, v140, v141
	v_cvt_pk_bf16_f32 v213, v142, v143
	s_nop 1
	v_permlane16_swap_b32_e32 v210, v212
	v_permlane16_swap_b32_e32 v211, v213
	s_nop 1
	global_store_dwordx4 v228, v[210:213], s[90:91] offset:128
	s_add_u32 s90, s90, s81
	s_addc_u32 s91, s91, 0
	v_mul_f32_e32 v136, 0xbfb8aa3b, v116
	v_mul_f32_e32 v137, 0xbfb8aa3b, v117
	v_mul_f32_e32 v138, 0xbfb8aa3b, v118
	v_mul_f32_e32 v139, 0xbfb8aa3b, v119
	v_mul_f32_e32 v140, 0xbfb8aa3b, v108
	v_mul_f32_e32 v141, 0xbfb8aa3b, v109
	v_mul_f32_e32 v142, 0xbfb8aa3b, v110
	v_mul_f32_e32 v143, 0xbfb8aa3b, v111
	v_exp_f32_e32 v136, v136
	v_exp_f32_e32 v137, v137
	v_exp_f32_e32 v138, v138
	v_exp_f32_e32 v139, v139
	v_exp_f32_e32 v140, v140
	v_exp_f32_e32 v141, v141
	v_exp_f32_e32 v142, v142
	v_exp_f32_e32 v143, v143
	v_add_f32_e32 v136, 1.0, v136
	v_add_f32_e32 v137, 1.0, v137
	v_add_f32_e32 v138, 1.0, v138
	v_add_f32_e32 v139, 1.0, v139
	v_add_f32_e32 v140, 1.0, v140
	v_add_f32_e32 v141, 1.0, v141
	v_add_f32_e32 v142, 1.0, v142
	v_add_f32_e32 v143, 1.0, v143
	v_rcp_f32_e32 v136, v136
	v_rcp_f32_e32 v137, v137
	v_rcp_f32_e32 v138, v138
	v_rcp_f32_e32 v139, v139
	v_rcp_f32_e32 v140, v140
	v_rcp_f32_e32 v141, v141
	v_rcp_f32_e32 v142, v142
	v_rcp_f32_e32 v143, v143
	v_mul_f32_e32 v136, v116, v136
	v_mul_f32_e32 v137, v117, v137
	v_mul_f32_e32 v138, v118, v138
	v_mul_f32_e32 v139, v119, v139
	v_mul_f32_e32 v140, v108, v140
	v_mul_f32_e32 v141, v109, v141
	v_mul_f32_e32 v142, v110, v142
	v_mul_f32_e32 v143, v111, v143
	v_mul_f32_e32 v136, v112, v136
	v_mul_f32_e32 v137, v113, v137
	v_mul_f32_e32 v138, v114, v138
	v_mul_f32_e32 v139, v115, v139
	v_mul_f32_e32 v140, v104, v140
	v_mul_f32_e32 v141, v105, v141
	v_mul_f32_e32 v142, v106, v142
	v_mul_f32_e32 v143, v107, v143
	v_cvt_pk_bf16_f32 v246, v136, v137
	v_cvt_pk_bf16_f32 v247, v138, v139
; __device__ __forceinline__ unsigned cvtpk(float lo, float hi) { f32x2 v = {lo, hi}; bf16x2_t b = __builtin_convertvector(v, bf16x2_t); return __builtin_bit_cast(unsigned, b); }
; __device__ __forceinline__ float sigmoidf_(float x) { return fast_rcp(1.f + __expf(-x)); }
;     __device__ __forceinline__ void operator()(const f32x4 (&acc)[2][2][4][2], const Unit& u, int wr, int wc, int fr, int fq) const {
;     ...
;             for (int ai = 0; ai < 2; ++ai)
; #pragma unroll
;                 for (int bj = 0; bj < 2; ++bj) { const int acol = ((u.pn * BM + bj * HALF + wc * 32) >> 1) + 4 * (fq - par);
; #pragma unroll
;                     for (int mp = 0; mp < 4; mp += 2) {
;                         u32x2 wk[2];
; #pragma unroll
;                         for (int q = 0; q < 2; ++q) { const f32x4 v0 = acc[ai][bj][mp + q][0], v1 = acc[ai][bj][mp + q][1]; float r[4];
; #pragma unroll
;                             for (int e = 0; e < 4; ++e) r[e] = v0[e] * sigmoidf_(v0[e]) * v1[e];
;                             wk[q].x = cvtpk(r[0], r[1]); wk[q].y = cvtpk(r[2], r[3]); }
;                         const auto sx = __builtin_amdgcn_permlane16_swap(wk[0].x, wk[1].x, false, false);
;                         const auto sy = __builtin_amdgcn_permlane16_swap(wk[0].y, wk[1].y, false, false);
;                         u32x4 w; w.x = sx[0]; w.y = sy[0]; w.z = sx[1]; w.w = sy[1];
;                         const size_t row = (size_t)(u.pm * BM + rl0 + ai * HALF + (mp + par) * 16);
;                         *(u32x4*)(O + row * ldc + acol) = w; } }
	v_cvt_pk_bf16_f32 v248, v140, v141
	v_cvt_pk_bf16_f32 v249, v142, v143
	s_nop 1
	v_permlane16_swap_b32_e32 v246, v248
	v_permlane16_swap_b32_e32 v247, v249
	s_nop 1
	global_store_dwordx4 v228, v[246:249], s[90:91]
	v_mul_f32_e32 v136, 0xbfb8aa3b, v84
	v_mul_f32_e32 v137, 0xbfb8aa3b, v85
	v_mul_f32_e32 v138, 0xbfb8aa3b, v86
	v_mul_f32_e32 v139, 0xbfb8aa3b, v87
	v_mul_f32_e32 v140, 0xbfb8aa3b, v76
	v_mul_f32_e32 v141, 0xbfb8aa3b, v77
	v_mul_f32_e32 v142, 0xbfb8aa3b, v78
	v_mul_f32_e32 v143, 0xbfb8aa3b, v79
	v_exp_f32_e32 v136, v136
	v_exp_f32_e32 v137, v137
	v_exp_f32_e32 v138, v138
	v_exp_f32_e32 v139, v139
	v_exp_f32_e32 v140, v140
	v_exp_f32_e32 v141, v141
	v_exp_f32_e32 v142, v142
	v_exp_f32_e32 v143, v143
	v_add_f32_e32 v136, 1.0, v136
	v_add_f32_e32 v137, 1.0, v137
	v_add_f32_e32 v138, 1.0, v138
	v_add_f32_e32 v139, 1.0, v139
	v_add_f32_e32 v140, 1.0, v140
	v_add_f32_e32 v141, 1.0, v141
	v_add_f32_e32 v142, 1.0, v142
	v_add_f32_e32 v143, 1.0, v143
	v_rcp_f32_e32 v136, v136
	v_rcp_f32_e32 v137, v137
	v_rcp_f32_e32 v138, v138
	v_rcp_f32_e32 v139, v139
	v_rcp_f32_e32 v140, v140
	v_rcp_f32_e32 v141, v141
	v_rcp_f32_e32 v142, v142
	v_rcp_f32_e32 v143, v143
	v_mul_f32_e32 v136, v84, v136
	v_mul_f32_e32 v137, v85, v137
	v_mul_f32_e32 v138, v86, v138
	v_mul_f32_e32 v139, v87, v139
	v_mul_f32_e32 v140, v76, v140
	v_mul_f32_e32 v141, v77, v141
	v_mul_f32_e32 v142, v78, v142
	v_mul_f32_e32 v143, v79, v143
	v_mul_f32_e32 v136, v80, v136
	v_mul_f32_e32 v137, v81, v137
	v_mul_f32_e32 v138, v82, v138
	v_mul_f32_e32 v139, v83, v139
	v_mul_f32_e32 v140, v72, v140
	v_mul_f32_e32 v141, v73, v141
	v_mul_f32_e32 v142, v74, v142
	v_mul_f32_e32 v143, v75, v143
	v_cvt_pk_bf16_f32 v210, v136, v137
	v_cvt_pk_bf16_f32 v211, v138, v139
	v_cvt_pk_bf16_f32 v212, v140, v141
	v_cvt_pk_bf16_f32 v213, v142, v143
	s_nop 1
	v_permlane16_swap_b32_e32 v210, v212
	v_permlane16_swap_b32_e32 v211, v213
	s_nop 1
	global_store_dwordx4 v228, v[210:213], s[90:91] offset:128
	s_add_u32 s90, s78, s80
	s_addc_u32 s91, s79, 0
	v_mul_f32_e32 v136, 0xbfb8aa3b, v68
	v_mul_f32_e32 v137, 0xbfb8aa3b, v69
	v_mul_f32_e32 v138, 0xbfb8aa3b, v70
	v_mul_f32_e32 v139, 0xbfb8aa3b, v71
	v_mul_f32_e32 v140, 0xbfb8aa3b, v60
	v_mul_f32_e32 v141, 0xbfb8aa3b, v61
	v_mul_f32_e32 v142, 0xbfb8aa3b, v62
	v_mul_f32_e32 v143, 0xbfb8aa3b, v63
	v_exp_f32_e32 v136, v136
	v_exp_f32_e32 v137, v137
	v_exp_f32_e32 v138, v138
	v_exp_f32_e32 v139, v139
	v_exp_f32_e32 v140, v140
	v_exp_f32_e32 v141, v141
	v_exp_f32_e32 v142, v142
	v_exp_f32_e32 v143, v143
	v_add_f32_e32 v136, 1.0, v136
	v_add_f32_e32 v137, 1.0, v137
	v_add_f32_e32 v138, 1.0, v138
	v_add_f32_e32 v139, 1.0, v139
	v_add_f32_e32 v140, 1.0, v140
	v_add_f32_e32 v141, 1.0, v141
	v_add_f32_e32 v142, 1.0, v142
	v_add_f32_e32 v143, 1.0, v143
	v_rcp_f32_e32 v136, v136
	v_rcp_f32_e32 v137, v137
	v_rcp_f32_e32 v138, v138
	v_rcp_f32_e32 v139, v139
	v_rcp_f32_e32 v140, v140
	v_rcp_f32_e32 v141, v141
	v_rcp_f32_e32 v142, v142
	v_rcp_f32_e32 v143, v143
	v_mul_f32_e32 v136, v68, v136
	v_mul_f32_e32 v137, v69, v137
	v_mul_f32_e32 v138, v70, v138
	v_mul_f32_e32 v139, v71, v139
	v_mul_f32_e32 v140, v60, v140
	v_mul_f32_e32 v141, v61, v141
	v_mul_f32_e32 v142, v62, v142
	v_mul_f32_e32 v143, v63, v143
	v_mul_f32_e32 v136, v64, v136
	v_mul_f32_e32 v137, v65, v137
	v_mul_f32_e32 v138, v66, v138
	v_mul_f32_e32 v139, v67, v139
	v_mul_f32_e32 v140, v56, v140
	v_mul_f32_e32 v141, v57, v141
	v_mul_f32_e32 v142, v58, v142
	v_mul_f32_e32 v143, v59, v143
	v_cvt_pk_bf16_f32 v246, v136, v137
	v_cvt_pk_bf16_f32 v247, v138, v139
	v_cvt_pk_bf16_f32 v248, v140, v141
	v_cvt_pk_bf16_f32 v249, v142, v143
	s_nop 1
	v_permlane16_swap_b32_e32 v246, v248
	v_permlane16_swap_b32_e32 v247, v249
	s_nop 1
	global_store_dwordx4 v228, v[246:249], s[90:91]
	v_mul_f32_e32 v136, 0xbfb8aa3b, v36
	v_mul_f32_e32 v137, 0xbfb8aa3b, v37
	v_mul_f32_e32 v138, 0xbfb8aa3b, v38
	v_mul_f32_e32 v139, 0xbfb8aa3b, v39
	v_mul_f32_e32 v140, 0xbfb8aa3b, v28
	v_mul_f32_e32 v141, 0xbfb8aa3b, v29
	v_mul_f32_e32 v142, 0xbfb8aa3b, v30
	v_mul_f32_e32 v143, 0xbfb8aa3b, v31
	v_exp_f32_e32 v136, v136
	v_exp_f32_e32 v137, v137
	v_exp_f32_e32 v138, v138
	v_exp_f32_e32 v139, v139
	v_exp_f32_e32 v140, v140
	v_exp_f32_e32 v141, v141
	v_exp_f32_e32 v142, v142
	v_exp_f32_e32 v143, v143
	v_add_f32_e32 v136, 1.0, v136
	v_add_f32_e32 v137, 1.0, v137
	v_add_f32_e32 v138, 1.0, v138
	v_add_f32_e32 v139, 1.0, v139
	v_add_f32_e32 v140, 1.0, v140
	v_add_f32_e32 v141, 1.0, v141
	v_add_f32_e32 v142, 1.0, v142
	v_add_f32_e32 v143, 1.0, v143
	v_rcp_f32_e32 v136, v136
; __device__ __forceinline__ unsigned cvtpk(float lo, float hi) { f32x2 v = {lo, hi}; bf16x2_t b = __builtin_convertvector(v, bf16x2_t); return __builtin_bit_cast(unsigned, b); }
; __device__ __forceinline__ float sigmoidf_(float x) { return fast_rcp(1.f + __expf(-x)); }
;     __device__ __forceinline__ void operator()(const f32x4 (&acc)[2][2][4][2], const Unit& u, int wr, int wc, int fr, int fq) const {
;     ...
;             for (int ai = 0; ai < 2; ++ai)
; #pragma unroll
;                 for (int bj = 0; bj < 2; ++bj) { const int acol = ((u.pn * BM + bj * HALF + wc * 32) >> 1) + 4 * (fq - par);
; #pragma unroll
;                     for (int mp = 0; mp < 4; mp += 2) {
;                         u32x2 wk[2];
; #pragma unroll
;                         for (int q = 0; q < 2; ++q) { const f32x4 v0 = acc[ai][bj][mp + q][0], v1 = acc[ai][bj][mp + q][1]; float r[4];
; #pragma unroll
;                             for (int e = 0; e < 4; ++e) r[e] = v0[e] * sigmoidf_(v0[e]) * v1[e];
;                             wk[q].x = cvtpk(r[0], r[1]); wk[q].y = cvtpk(r[2], r[3]); }
;                         const auto sx = __builtin_amdgcn_permlane16_swap(wk[0].x, wk[1].x, false, false);
;                         const auto sy = __builtin_amdgcn_permlane16_swap(wk[0].y, wk[1].y, false, false);
;                         u32x4 w; w.x = sx[0]; w.y = sy[0]; w.z = sx[1]; w.w = sy[1];
;                         const size_t row = (size_t)(u.pm * BM + rl0 + ai * HALF + (mp + par) * 16);
;                         *(u32x4*)(O + row * ldc + acol) = w; } }
;             return;
	v_rcp_f32_e32 v137, v137
	v_rcp_f32_e32 v138, v138
	v_rcp_f32_e32 v139, v139
	v_rcp_f32_e32 v140, v140
	v_rcp_f32_e32 v141, v141
	v_rcp_f32_e32 v142, v142
	v_rcp_f32_e32 v143, v143
	v_mul_f32_e32 v136, v36, v136
	v_mul_f32_e32 v137, v37, v137
	v_mul_f32_e32 v138, v38, v138
	v_mul_f32_e32 v139, v39, v139
	v_mul_f32_e32 v140, v28, v140
	v_mul_f32_e32 v141, v29, v141
	v_mul_f32_e32 v142, v30, v142
	v_mul_f32_e32 v143, v31, v143
	v_mul_f32_e32 v136, v32, v136
	v_mul_f32_e32 v137, v33, v137
	v_mul_f32_e32 v138, v34, v138
	v_mul_f32_e32 v139, v35, v139
	v_mul_f32_e32 v140, v24, v140
	v_mul_f32_e32 v141, v25, v141
	v_mul_f32_e32 v142, v26, v142
	v_mul_f32_e32 v143, v27, v143
	v_cvt_pk_bf16_f32 v210, v136, v137
	v_cvt_pk_bf16_f32 v211, v138, v139
	v_cvt_pk_bf16_f32 v212, v140, v141
	v_cvt_pk_bf16_f32 v213, v142, v143
	s_nop 1
	v_permlane16_swap_b32_e32 v210, v212
	v_permlane16_swap_b32_e32 v211, v213
	s_nop 1
	global_store_dwordx4 v228, v[210:213], s[90:91] offset:128
	s_add_u32 s90, s90, s81
	s_addc_u32 s91, s91, 0
	v_mul_f32_e32 v136, 0xbfb8aa3b, v52
	v_mul_f32_e32 v137, 0xbfb8aa3b, v53
	v_mul_f32_e32 v138, 0xbfb8aa3b, v54
	v_mul_f32_e32 v139, 0xbfb8aa3b, v55
	v_mul_f32_e32 v140, 0xbfb8aa3b, v44
	v_mul_f32_e32 v141, 0xbfb8aa3b, v45
	v_mul_f32_e32 v142, 0xbfb8aa3b, v46
	v_mul_f32_e32 v143, 0xbfb8aa3b, v47
	v_exp_f32_e32 v136, v136
	v_exp_f32_e32 v137, v137
	v_exp_f32_e32 v138, v138
	v_exp_f32_e32 v139, v139
	v_exp_f32_e32 v140, v140
	v_exp_f32_e32 v141, v141
	v_exp_f32_e32 v142, v142
	v_exp_f32_e32 v143, v143
	v_add_f32_e32 v136, 1.0, v136
	v_add_f32_e32 v137, 1.0, v137
	v_add_f32_e32 v138, 1.0, v138
	v_add_f32_e32 v139, 1.0, v139
	v_add_f32_e32 v140, 1.0, v140
	v_add_f32_e32 v141, 1.0, v141
	v_add_f32_e32 v142, 1.0, v142
	v_add_f32_e32 v143, 1.0, v143
	v_rcp_f32_e32 v136, v136
	v_rcp_f32_e32 v137, v137
	v_rcp_f32_e32 v138, v138
	v_rcp_f32_e32 v139, v139
	v_rcp_f32_e32 v140, v140
	v_rcp_f32_e32 v141, v141
	v_rcp_f32_e32 v142, v142
	v_rcp_f32_e32 v143, v143
	v_mul_f32_e32 v136, v52, v136
	v_mul_f32_e32 v137, v53, v137
	v_mul_f32_e32 v138, v54, v138
	v_mul_f32_e32 v139, v55, v139
	v_mul_f32_e32 v140, v44, v140
	v_mul_f32_e32 v141, v45, v141
	v_mul_f32_e32 v142, v46, v142
	v_mul_f32_e32 v143, v47, v143
	v_mul_f32_e32 v136, v48, v136
	v_mul_f32_e32 v137, v49, v137
	v_mul_f32_e32 v138, v50, v138
	v_mul_f32_e32 v139, v51, v139
	v_mul_f32_e32 v140, v40, v140
	v_mul_f32_e32 v141, v41, v141
	v_mul_f32_e32 v142, v42, v142
	v_mul_f32_e32 v143, v43, v143
	v_cvt_pk_bf16_f32 v246, v136, v137
	v_cvt_pk_bf16_f32 v247, v138, v139
	v_cvt_pk_bf16_f32 v248, v140, v141
	v_cvt_pk_bf16_f32 v249, v142, v143
	s_nop 1
	v_permlane16_swap_b32_e32 v246, v248
	v_permlane16_swap_b32_e32 v247, v249
	s_nop 1
	global_store_dwordx4 v228, v[246:249], s[90:91]
	v_mul_f32_e32 v136, 0xbfb8aa3b, v20
	v_mul_f32_e32 v137, 0xbfb8aa3b, v21
	v_mul_f32_e32 v138, 0xbfb8aa3b, v22
	v_mul_f32_e32 v139, 0xbfb8aa3b, v23
	v_mul_f32_e32 v140, 0xbfb8aa3b, v12
	v_mul_f32_e32 v141, 0xbfb8aa3b, v13
	v_mul_f32_e32 v142, 0xbfb8aa3b, v14
	v_mul_f32_e32 v143, 0xbfb8aa3b, v15
	v_exp_f32_e32 v136, v136
	v_exp_f32_e32 v137, v137
	v_exp_f32_e32 v138, v138
	v_exp_f32_e32 v139, v139
	v_exp_f32_e32 v140, v140
	v_exp_f32_e32 v141, v141
	v_exp_f32_e32 v142, v142
	v_exp_f32_e32 v143, v143
	v_add_f32_e32 v136, 1.0, v136
	v_add_f32_e32 v137, 1.0, v137
	v_add_f32_e32 v138, 1.0, v138
	v_add_f32_e32 v139, 1.0, v139
	v_add_f32_e32 v140, 1.0, v140
	v_add_f32_e32 v141, 1.0, v141
	v_add_f32_e32 v142, 1.0, v142
	v_add_f32_e32 v143, 1.0, v143
	v_rcp_f32_e32 v136, v136
	v_rcp_f32_e32 v137, v137
	v_rcp_f32_e32 v138, v138
	v_rcp_f32_e32 v139, v139
	v_rcp_f32_e32 v140, v140
	v_rcp_f32_e32 v141, v141
	v_rcp_f32_e32 v142, v142
	v_rcp_f32_e32 v143, v143
	v_mul_f32_e32 v136, v20, v136
	v_mul_f32_e32 v137, v21, v137
	v_mul_f32_e32 v138, v22, v138
	v_mul_f32_e32 v139, v23, v139
	v_mul_f32_e32 v140, v12, v140
	v_mul_f32_e32 v141, v13, v141
	v_mul_f32_e32 v142, v14, v142
	v_mul_f32_e32 v143, v15, v143
	v_mul_f32_e32 v136, v16, v136
	v_mul_f32_e32 v137, v17, v137
	v_mul_f32_e32 v138, v18, v138
	v_mul_f32_e32 v139, v19, v139
	v_mul_f32_e32 v140, v8, v140
	v_mul_f32_e32 v141, v9, v141
	v_mul_f32_e32 v142, v10, v142
	v_mul_f32_e32 v143, v11, v143
	v_cvt_pk_bf16_f32 v210, v136, v137
	v_cvt_pk_bf16_f32 v211, v138, v139
	v_cvt_pk_bf16_f32 v212, v140, v141
	v_cvt_pk_bf16_f32 v213, v142, v143
	s_nop 1
	v_permlane16_swap_b32_e32 v210, v212
	v_permlane16_swap_b32_e32 v211, v213
	s_nop 1
	global_store_dwordx4 v228, v[210:213], s[90:91] offset:128
	s_branch .LBB0_422
